# phase 4 epilogue: residual-input loads issued together up front (counted vmcnt) instead of 16 serialised load-use round trips per unit
# speedup vs baseline: 1.0146x; 1.0005x over previous
.LBB0_450:
	s_ashr_i32 s29, s42, 3
	s_mul_hi_i32 s31, s29, 0x6000
	s_mulk_i32 s29, 0x6000
	s_add_u32 s44, s75, s29
	v_lshl_add_u32 v158, s42, 8, v145
	v_lshl_or_b32 v156, s43, 8, v149
	s_addc_u32 s45, s76, s31
	v_ashrrev_i32_e32 v159, 31, v158
	v_ashrrev_i32_e32 v157, 31, v156
	s_cmpk_lt_i32 s42, 0x80
	v_lshlrev_b64 v[88:89], 10, v[158:159]
	s_cselect_b32 s43, s9, s82
	s_cselect_b32 s42, s8, s81
	v_lshl_add_u64 v[154:155], v[88:89], 0, v[156:157]
	v_lshl_add_u64 v[170:171], v[154:155], 2, s[42:43]
	v_lshl_add_u64 v[100:101], v[156:157], 2, s[44:45]
	global_load_dwordx4 v[108:111], v[100:101], off
	global_load_dwordx4 v[104:107], v[100:101], off offset:16
	v_lshlrev_b32_e32 v206, 2, v154
	s_mov_b32 s98, s42
	s_mov_b32 s99, s43
	global_load_dwordx4 v[174:177], v206, s[98:99]
	global_load_dwordx4 v[178:181], v206, s[98:99] offset:16
	s_mov_b32 s98, s42
	s_mov_b32 s99, s43
	global_load_dwordx4 v[182:185], v206, s[98:99] offset:512
	global_load_dwordx4 v[186:189], v206, s[98:99] offset:528
	s_add_u32 s98, s42, 0x10000
	s_addc_u32 s99, s43, 0
	global_load_dwordx4 v[190:193], v206, s[98:99]
	global_load_dwordx4 v[194:197], v206, s[98:99] offset:16
	s_add_u32 s98, s42, 0x10000
	s_addc_u32 s99, s43, 0
	global_load_dwordx4 v[198:201], v206, s[98:99] offset:512
	global_load_dwordx4 v[202:205], v206, s[98:99] offset:528
	s_add_u32 s98, s42, 0x20000
	s_addc_u32 s99, s43, 0
	global_load_dwordx4 v[214:217], v206, s[98:99]
	global_load_dwordx4 v[218:221], v206, s[98:99] offset:16
	s_add_u32 s98, s42, 0x20000
	s_addc_u32 s99, s43, 0
	global_load_dwordx4 v[222:225], v206, s[98:99] offset:512
	global_load_dwordx4 v[226:229], v206, s[98:99] offset:528
	s_add_u32 s98, s42, 0x30000
	s_addc_u32 s99, s43, 0
	global_load_dwordx4 v[230:233], v206, s[98:99]
	global_load_dwordx4 v[234:237], v206, s[98:99] offset:16
	s_add_u32 s98, s42, 0x30000
	s_addc_u32 s99, s43, 0
	global_load_dwordx4 v[238:241], v206, s[98:99] offset:512
	global_load_dwordx4 v[242:245], v206, s[98:99] offset:528
	v_lshl_add_u64 v[172:173], v[154:155], 1, s[14:15]
	global_load_dwordx4 v[88:91], v[100:101], off offset:528
	s_nop 0
	global_load_dwordx4 v[100:103], v[100:101], off offset:512
	s_andn2_b64 vcc, exec, s[4:5]
	s_mov_b64 s[4:5], -1
	s_waitcnt vmcnt(0)
	v_mov_b64_e32 v[162:163], v[174:175]
	v_mov_b64_e32 v[164:165], v[176:177]
	v_mov_b64_e32 v[166:167], v[178:179]
	v_mov_b64_e32 v[168:169], v[180:181]
	v_pk_fma_f32 v[140:141], v[140:141], v[108:109], v[162:163]
	v_pk_fma_f32 v[142:143], v[142:143], v[110:111], v[164:165]
	v_pk_fma_f32 v[162:163], v[138:139], v[106:107], v[168:169]
	v_pk_fma_f32 v[138:139], v[136:137], v[104:105], v[166:167]
	v_cvt_pk_bf16_f32 v136, v140, v141
	v_cvt_pk_bf16_f32 v137, v142, v143
	s_nop 0
	v_cvt_pk_bf16_f32 v138, v138, v139
	v_cvt_pk_bf16_f32 v139, v162, v163
	global_store_dwordx4 v[172:173], v[136:139], off
	s_add_u32 s98, s42, 0x80000
	s_addc_u32 s99, s43, 0
	global_load_dwordx4 v[174:177], v206, s[98:99]
	global_load_dwordx4 v[178:181], v206, s[98:99] offset:16
	s_nop 1
	v_mov_b64_e32 v[136:137], v[182:183]
	v_mov_b64_e32 v[138:139], v[184:185]
	s_nop 0
	v_mov_b64_e32 v[140:141], v[186:187]
	v_mov_b64_e32 v[142:143], v[188:189]
	v_or_b32_e32 v162, 16, v158
	v_ashrrev_i32_e32 v163, 31, v162
	v_lshlrev_b64 v[162:163], 10, v[162:163]
	v_lshl_add_u64 v[162:163], v[162:163], 0, v[156:157]
	v_lshl_add_u64 v[164:165], v[162:163], 2, s[42:43]
	s_nop 0
	v_pk_fma_f32 v[132:133], v[132:133], v[100:101], v[136:137]
	s_nop 0
	v_pk_fma_f32 v[136:137], v[130:131], v[90:91], v[142:143]
	v_pk_fma_f32 v[130:131], v[128:129], v[88:89], v[140:141]
	v_pk_fma_f32 v[134:135], v[134:135], v[102:103], v[138:139]
	v_cvt_pk_bf16_f32 v128, v132, v133
	s_nop 0
	v_cvt_pk_bf16_f32 v129, v134, v135
	v_cvt_pk_bf16_f32 v130, v130, v131
	v_cvt_pk_bf16_f32 v131, v136, v137
	global_store_dwordx4 v[172:173], v[128:131], off offset:256
	s_add_u32 s98, s42, 0x80000
	s_addc_u32 s99, s43, 0
	global_load_dwordx4 v[182:185], v206, s[98:99] offset:512
	global_load_dwordx4 v[186:189], v206, s[98:99] offset:528
	s_nop 1
	v_mov_b64_e32 v[128:129], v[190:191]
	v_mov_b64_e32 v[130:131], v[192:193]
	s_nop 0
	v_mov_b64_e32 v[132:133], v[194:195]
	v_mov_b64_e32 v[134:135], v[196:197]
	v_lshl_add_u64 v[136:137], v[162:163], 1, s[14:15]
	s_nop 0
	v_pk_fma_f32 v[124:125], v[124:125], v[108:109], v[128:129]
	s_nop 0
	v_pk_fma_f32 v[128:129], v[122:123], v[106:107], v[134:135]
	v_pk_fma_f32 v[122:123], v[120:121], v[104:105], v[132:133]
	v_pk_fma_f32 v[126:127], v[126:127], v[110:111], v[130:131]
	v_cvt_pk_bf16_f32 v120, v124, v125
	s_nop 0
	v_cvt_pk_bf16_f32 v121, v126, v127
	v_cvt_pk_bf16_f32 v122, v122, v123
	v_cvt_pk_bf16_f32 v123, v128, v129
	global_store_dwordx4 v[136:137], v[120:123], off
	s_add_u32 s98, s42, 0x90000
	s_addc_u32 s99, s43, 0
	global_load_dwordx4 v[190:193], v206, s[98:99]
	global_load_dwordx4 v[194:197], v206, s[98:99] offset:16
	s_nop 1
	v_mov_b64_e32 v[120:121], v[198:199]
	v_mov_b64_e32 v[122:123], v[200:201]
	s_nop 0
	v_mov_b64_e32 v[124:125], v[202:203]
	v_mov_b64_e32 v[126:127], v[204:205]
	v_or_b32_e32 v128, 32, v158
	v_ashrrev_i32_e32 v129, 31, v128
	v_lshlrev_b64 v[128:129], 10, v[128:129]
	v_lshl_add_u64 v[128:129], v[128:129], 0, v[156:157]
	v_lshl_add_u64 v[130:131], v[128:129], 2, s[42:43]
	s_nop 0
	v_pk_fma_f32 v[116:117], v[116:117], v[100:101], v[120:121]
	s_nop 0
	v_pk_fma_f32 v[120:121], v[114:115], v[90:91], v[126:127]
	v_pk_fma_f32 v[114:115], v[112:113], v[88:89], v[124:125]
	v_pk_fma_f32 v[118:119], v[118:119], v[102:103], v[122:123]
	v_cvt_pk_bf16_f32 v112, v116, v117
	s_nop 0
	v_cvt_pk_bf16_f32 v113, v118, v119
	v_cvt_pk_bf16_f32 v114, v114, v115
	v_cvt_pk_bf16_f32 v115, v120, v121
	global_store_dwordx4 v[136:137], v[112:115], off offset:256
	s_add_u32 s98, s42, 0x90000
	s_addc_u32 s99, s43, 0
	global_load_dwordx4 v[198:201], v206, s[98:99] offset:512
	global_load_dwordx4 v[202:205], v206, s[98:99] offset:528
	s_nop 1
	v_mov_b64_e32 v[112:113], v[214:215]
	v_mov_b64_e32 v[114:115], v[216:217]
	s_nop 0
	v_mov_b64_e32 v[116:117], v[218:219]
	v_mov_b64_e32 v[118:119], v[220:221]
	v_lshl_add_u64 v[120:121], v[128:129], 1, s[14:15]
	s_nop 0
	v_pk_fma_f32 v[96:97], v[96:97], v[108:109], v[112:113]
	s_nop 0
	v_pk_fma_f32 v[112:113], v[94:95], v[106:107], v[118:119]
	v_pk_fma_f32 v[94:95], v[92:93], v[104:105], v[116:117]
	v_pk_fma_f32 v[98:99], v[98:99], v[110:111], v[114:115]
	v_cvt_pk_bf16_f32 v92, v96, v97
	s_nop 0
	v_cvt_pk_bf16_f32 v93, v98, v99
	v_cvt_pk_bf16_f32 v94, v94, v95
	v_cvt_pk_bf16_f32 v95, v112, v113
	global_store_dwordx4 v[120:121], v[92:95], off
	s_add_u32 s98, s42, 0xa0000
	s_addc_u32 s99, s43, 0
	global_load_dwordx4 v[214:217], v206, s[98:99]
	global_load_dwordx4 v[218:221], v206, s[98:99] offset:16
	s_nop 1
	v_mov_b64_e32 v[92:93], v[222:223]
	v_mov_b64_e32 v[94:95], v[224:225]
	s_nop 0
	v_mov_b64_e32 v[96:97], v[226:227]
	v_mov_b64_e32 v[98:99], v[228:229]
	v_or_b32_e32 v112, 48, v158
	v_ashrrev_i32_e32 v113, 31, v112
	v_lshlrev_b64 v[112:113], 10, v[112:113]
	v_lshl_add_u64 v[112:113], v[112:113], 0, v[156:157]
	v_lshl_add_u64 v[114:115], v[112:113], 2, s[42:43]
	s_nop 0
	v_pk_fma_f32 v[84:85], v[84:85], v[100:101], v[92:93]
	s_nop 0
	v_pk_fma_f32 v[92:93], v[82:83], v[90:91], v[98:99]
	v_pk_fma_f32 v[82:83], v[80:81], v[88:89], v[96:97]
	v_pk_fma_f32 v[86:87], v[86:87], v[102:103], v[94:95]
	v_cvt_pk_bf16_f32 v80, v84, v85
	s_nop 0
	v_cvt_pk_bf16_f32 v81, v86, v87
	v_cvt_pk_bf16_f32 v82, v82, v83
	v_cvt_pk_bf16_f32 v83, v92, v93
	global_store_dwordx4 v[120:121], v[80:83], off offset:256
	s_add_u32 s98, s42, 0xa0000
	s_addc_u32 s99, s43, 0
	global_load_dwordx4 v[222:225], v206, s[98:99] offset:512
	global_load_dwordx4 v[226:229], v206, s[98:99] offset:528
	s_nop 1
	v_mov_b64_e32 v[80:81], v[230:231]
	v_mov_b64_e32 v[82:83], v[232:233]
	s_nop 0
	v_mov_b64_e32 v[84:85], v[234:235]
	v_mov_b64_e32 v[86:87], v[236:237]
	v_lshl_add_u64 v[92:93], v[112:113], 1, s[14:15]
	s_nop 0
	v_pk_fma_f32 v[76:77], v[76:77], v[108:109], v[80:81]
	s_nop 0
	v_pk_fma_f32 v[80:81], v[74:75], v[106:107], v[86:87]
	v_pk_fma_f32 v[74:75], v[72:73], v[104:105], v[84:85]
	v_pk_fma_f32 v[78:79], v[78:79], v[110:111], v[82:83]
	v_cvt_pk_bf16_f32 v72, v76, v77
	s_nop 0
	v_cvt_pk_bf16_f32 v73, v78, v79
	v_cvt_pk_bf16_f32 v74, v74, v75
	v_cvt_pk_bf16_f32 v75, v80, v81
	global_store_dwordx4 v[92:93], v[72:75], off
	s_add_u32 s98, s42, 0xb0000
	s_addc_u32 s99, s43, 0
	global_load_dwordx4 v[230:233], v206, s[98:99]
	global_load_dwordx4 v[234:237], v206, s[98:99] offset:16
	s_nop 1
	v_mov_b64_e32 v[72:73], v[238:239]
	v_mov_b64_e32 v[74:75], v[240:241]
	s_nop 0
	v_mov_b64_e32 v[76:77], v[242:243]
	v_mov_b64_e32 v[78:79], v[244:245]
	v_lshl_add_u64 v[80:81], v[154:155], 0, s[10:11]
	v_lshl_add_u64 v[82:83], v[80:81], 2, s[42:43]
	s_nop 0
	v_pk_fma_f32 v[60:61], v[60:61], v[100:101], v[72:73]
	s_nop 0
	v_pk_fma_f32 v[72:73], v[58:59], v[90:91], v[78:79]
	v_pk_fma_f32 v[58:59], v[56:57], v[88:89], v[76:77]
	v_pk_fma_f32 v[62:63], v[62:63], v[102:103], v[74:75]
	v_cvt_pk_bf16_f32 v56, v60, v61
	s_nop 0
	v_cvt_pk_bf16_f32 v57, v62, v63
	v_cvt_pk_bf16_f32 v58, v58, v59
	v_cvt_pk_bf16_f32 v59, v72, v73
	global_store_dwordx4 v[92:93], v[56:59], off offset:256
	s_add_u32 s98, s42, 0xb0000
	s_addc_u32 s99, s43, 0
	global_load_dwordx4 v[238:241], v206, s[98:99] offset:512
	global_load_dwordx4 v[242:245], v206, s[98:99] offset:528
	s_waitcnt vmcnt(21)
	s_nop 1
	v_mov_b64_e32 v[56:57], v[174:175]
	v_mov_b64_e32 v[58:59], v[176:177]
	s_nop 0
	v_mov_b64_e32 v[60:61], v[178:179]
	v_mov_b64_e32 v[62:63], v[180:181]
	v_lshl_add_u64 v[72:73], v[80:81], 1, s[14:15]
	s_nop 0
	v_pk_fma_f32 v[58:59], v[70:71], v[110:111], v[58:59]
	v_pk_fma_f32 v[56:57], v[68:69], v[108:109], v[56:57]
	s_nop 0
	v_pk_fma_f32 v[62:63], v[66:67], v[106:107], v[62:63]
	v_pk_fma_f32 v[60:61], v[64:65], v[104:105], v[60:61]
	v_cvt_pk_bf16_f32 v56, v56, v57
	v_cvt_pk_bf16_f32 v57, v58, v59
	v_lshl_add_u64 v[64:65], v[154:155], 0, s[20:21]
	v_cvt_pk_bf16_f32 v58, v60, v61
	v_cvt_pk_bf16_f32 v59, v62, v63
	global_store_dwordx4 v[72:73], v[56:59], off
	s_waitcnt vmcnt(19)
	s_nop 1
	v_mov_b64_e32 v[56:57], v[182:183]
	v_mov_b64_e32 v[58:59], v[184:185]
	s_nop 0
	v_mov_b64_e32 v[60:61], v[186:187]
	v_mov_b64_e32 v[62:63], v[188:189]
	v_lshl_add_u64 v[66:67], v[64:65], 2, s[42:43]
	s_nop 0
	v_pk_fma_f32 v[52:53], v[52:53], v[100:101], v[56:57]
	s_nop 0
	v_pk_fma_f32 v[56:57], v[50:51], v[90:91], v[62:63]
	v_pk_fma_f32 v[50:51], v[48:49], v[88:89], v[60:61]
	v_pk_fma_f32 v[54:55], v[54:55], v[102:103], v[58:59]
	v_cvt_pk_bf16_f32 v48, v52, v53
	s_nop 0
	v_cvt_pk_bf16_f32 v49, v54, v55
	v_cvt_pk_bf16_f32 v50, v50, v51
	v_cvt_pk_bf16_f32 v51, v56, v57
	global_store_dwordx4 v[72:73], v[48:51], off offset:256
	s_waitcnt vmcnt(17)
	s_nop 1
	v_mov_b64_e32 v[48:49], v[190:191]
	v_mov_b64_e32 v[50:51], v[192:193]
	s_nop 0
	v_mov_b64_e32 v[52:53], v[194:195]
	v_mov_b64_e32 v[54:55], v[196:197]
	v_lshl_add_u64 v[56:57], v[64:65], 1, s[14:15]
	s_nop 0
	v_pk_fma_f32 v[44:45], v[44:45], v[108:109], v[48:49]
	s_nop 0
	v_pk_fma_f32 v[48:49], v[42:43], v[106:107], v[54:55]
	v_pk_fma_f32 v[42:43], v[40:41], v[104:105], v[52:53]
	v_pk_fma_f32 v[46:47], v[46:47], v[110:111], v[50:51]
	v_cvt_pk_bf16_f32 v40, v44, v45
	s_nop 0
	v_cvt_pk_bf16_f32 v41, v46, v47
	v_cvt_pk_bf16_f32 v42, v42, v43
	v_cvt_pk_bf16_f32 v43, v48, v49
	global_store_dwordx4 v[56:57], v[40:43], off
	s_waitcnt vmcnt(15)
	s_nop 1
	v_mov_b64_e32 v[40:41], v[198:199]
	v_mov_b64_e32 v[42:43], v[200:201]
	s_nop 0
	v_mov_b64_e32 v[44:45], v[202:203]
	v_mov_b64_e32 v[46:47], v[204:205]
	v_lshl_add_u64 v[48:49], v[154:155], 0, s[22:23]
	v_lshl_add_u64 v[50:51], v[48:49], 2, s[42:43]
	s_nop 0
	v_pk_fma_f32 v[36:37], v[36:37], v[100:101], v[40:41]
	s_nop 0
	v_pk_fma_f32 v[40:41], v[34:35], v[90:91], v[46:47]
	v_pk_fma_f32 v[34:35], v[32:33], v[88:89], v[44:45]
	v_pk_fma_f32 v[38:39], v[38:39], v[102:103], v[42:43]
	v_cvt_pk_bf16_f32 v32, v36, v37
	s_nop 0
	v_cvt_pk_bf16_f32 v33, v38, v39
	v_cvt_pk_bf16_f32 v34, v34, v35
	v_cvt_pk_bf16_f32 v35, v40, v41
	global_store_dwordx4 v[56:57], v[32:35], off offset:256
	s_waitcnt vmcnt(13)
	s_nop 1
	v_mov_b64_e32 v[32:33], v[214:215]
	v_mov_b64_e32 v[34:35], v[216:217]
	s_nop 0
	v_mov_b64_e32 v[36:37], v[218:219]
	v_mov_b64_e32 v[38:39], v[220:221]
	v_lshl_add_u64 v[40:41], v[48:49], 1, s[14:15]
	s_nop 0
	v_pk_fma_f32 v[28:29], v[28:29], v[108:109], v[32:33]
	s_nop 0
	v_pk_fma_f32 v[32:33], v[26:27], v[106:107], v[38:39]
	v_pk_fma_f32 v[26:27], v[24:25], v[104:105], v[36:37]
	v_pk_fma_f32 v[30:31], v[30:31], v[110:111], v[34:35]
	v_cvt_pk_bf16_f32 v24, v28, v29
	s_nop 0
	v_cvt_pk_bf16_f32 v25, v30, v31
	v_cvt_pk_bf16_f32 v26, v26, v27
	v_cvt_pk_bf16_f32 v27, v32, v33
	global_store_dwordx4 v[40:41], v[24:27], off
	s_waitcnt vmcnt(11)
	s_nop 1
	v_mov_b64_e32 v[24:25], v[222:223]
	v_mov_b64_e32 v[26:27], v[224:225]
	s_nop 0
	v_mov_b64_e32 v[28:29], v[226:227]
	v_mov_b64_e32 v[30:31], v[228:229]
	v_lshl_add_u64 v[32:33], v[154:155], 0, s[26:27]
	v_lshl_add_u64 v[34:35], v[32:33], 2, s[42:43]
	s_nop 0
	v_pk_fma_f32 v[20:21], v[20:21], v[100:101], v[24:25]
	s_nop 0
	v_pk_fma_f32 v[24:25], v[18:19], v[90:91], v[30:31]
	v_pk_fma_f32 v[18:19], v[16:17], v[88:89], v[28:29]
	v_pk_fma_f32 v[22:23], v[22:23], v[102:103], v[26:27]
	v_cvt_pk_bf16_f32 v16, v20, v21
	s_nop 0
	v_cvt_pk_bf16_f32 v17, v22, v23
	v_cvt_pk_bf16_f32 v18, v18, v19
	v_cvt_pk_bf16_f32 v19, v24, v25
	global_store_dwordx4 v[40:41], v[16:19], off offset:256
	s_waitcnt vmcnt(9)
	s_nop 1
	v_mov_b64_e32 v[16:17], v[230:231]
	v_mov_b64_e32 v[18:19], v[232:233]
	s_nop 0
	v_mov_b64_e32 v[20:21], v[234:235]
	v_mov_b64_e32 v[22:23], v[236:237]
	v_lshl_add_u64 v[24:25], v[32:33], 1, s[14:15]
	s_nop 0
	v_pk_fma_f32 v[12:13], v[12:13], v[108:109], v[16:17]
	s_nop 0
	v_pk_fma_f32 v[16:17], v[10:11], v[106:107], v[22:23]
	v_pk_fma_f32 v[10:11], v[8:9], v[104:105], v[20:21]
	v_pk_fma_f32 v[14:15], v[14:15], v[110:111], v[18:19]
	v_cvt_pk_bf16_f32 v8, v12, v13
	s_nop 0
	v_cvt_pk_bf16_f32 v9, v14, v15
	v_cvt_pk_bf16_f32 v10, v10, v11
	v_cvt_pk_bf16_f32 v11, v16, v17
	global_store_dwordx4 v[24:25], v[8:11], off
	s_waitcnt vmcnt(7)
	s_nop 1
	v_mov_b64_e32 v[8:9], v[238:239]
	v_mov_b64_e32 v[10:11], v[240:241]
	s_nop 0
	v_mov_b64_e32 v[12:13], v[242:243]
	v_mov_b64_e32 v[14:15], v[244:245]
	s_nop 0
	v_pk_fma_f32 v[4:5], v[4:5], v[100:101], v[8:9]
	s_nop 0
	v_pk_fma_f32 v[8:9], v[2:3], v[90:91], v[14:15]
	v_pk_fma_f32 v[2:3], v[0:1], v[88:89], v[12:13]
	v_pk_fma_f32 v[6:7], v[6:7], v[102:103], v[10:11]
	v_cvt_pk_bf16_f32 v0, v4, v5
	s_nop 0
	v_cvt_pk_bf16_f32 v1, v6, v7
	v_cvt_pk_bf16_f32 v2, v2, v3
	v_cvt_pk_bf16_f32 v3, v8, v9
	global_store_dwordx4 v[24:25], v[0:3], off offset:256
	s_cbranch_vccnz .LBB0_441
	s_andn2_b64 vcc, exec, s[12:13]
	s_mov_b64 s[50:51], s[40:41]
	s_cbranch_vccnz .LBB0_440
	s_mov_b64 s[50:51], s[40:41]
	s_barrier
	s_branch .LBB0_440
